# hgrn_c: state/V fragment loads and output-stage gate loads issued in batches; hgrn_a: V fragment loads hoisted above the barrier
# speedup vs baseline: 1.0416x; 1.0088x over previous
.LBB0_127:
	s_or_b64 exec, exec, s[4:5]
	v_mul_f32_e32 v20, v17, v17
	v_fmac_f32_e32 v20, v16, v16
	v_fmac_f32_e32 v20, v18, v18
	v_fmac_f32_e32 v20, v19, v19
	v_fmac_f32_e32 v20, v8, v8
	v_fmac_f32_e32 v20, v9, v9
	v_fmac_f32_e32 v20, v10, v10
	v_fmac_f32_e32 v20, v11, v11
	v_pk_mul_f32 v[14:15], v[4:5], v[4:5]
	v_pk_mul_f32 v[12:13], v[6:7], v[6:7]
	v_add_f32_e32 v14, v14, v20
	v_add_f32_e32 v14, v15, v14
	v_add_f32_e32 v12, v12, v14
	v_add_f32_e32 v20, v13, v12
	v_pk_mul_f32 v[14:15], v[0:1], v[0:1]
	v_pk_mul_f32 v[12:13], v[2:3], v[2:3]
	v_add_f32_e32 v14, v14, v20
	v_add_f32_e32 v14, v15, v14
	v_add_f32_e32 v12, v12, v14
	v_and_b32_e32 v14, 64, v200
	v_add_f32_e32 v12, v13, v12
	v_xor_b32_e32 v13, 16, v200
	v_add_u32_e32 v14, 64, v14
	v_cmp_lt_i32_e32 vcc, v13, v14
	s_ashr_i32 s15, s14, 31
	s_lshl_b64 s[4:5], s[14:15], 12
	v_cndmask_b32_e32 v13, v200, v13, vcc
	v_lshlrev_b32_e32 v13, 2, v13
	ds_bpermute_b32 v13, v13, v12
	s_or_b32 s4, s4, s26
	v_ashrrev_i32_e32 v29, 31, v28
	v_lshl_add_u64 v[22:23], v[30:31], 2, s[10:11]
	s_waitcnt lgkmcnt(0)
	v_add_f32_e32 v12, v12, v13
	v_xor_b32_e32 v13, 32, v200
	v_cmp_lt_i32_e32 vcc, v13, v14
	v_mov_b64_e32 v[14:15], s[92:93]
	s_nop 0
	v_cndmask_b32_e32 v13, v200, v13, vcc
	v_lshlrev_b32_e32 v13, 2, v13
	ds_bpermute_b32 v13, v13, v12
	s_waitcnt lgkmcnt(0)
	v_add_f32_e32 v12, v12, v13
	v_fmamk_f32 v12, v12, 0x3c800000, v199
	v_cmp_gt_f32_e32 vcc, s73, v12
	v_mul_f32_e32 v13, 0x4b800000, v12
	s_nop 0
	v_cndmask_b32_e32 v12, v12, v13, vcc
	v_rsq_f32_e32 v12, v12
	s_nop 0
	v_mul_f32_e32 v13, 0x45800000, v12
	v_cndmask_b32_e32 v24, v12, v13, vcc
	v_lshl_add_u64 v[12:13], s[4:5], 0, v[28:29]
	v_mad_u64_u32 v[14:15], s[4:5], v12, s63, v[14:15]
	v_mad_i32_i24 v15, v13, s63, v15
	v_lshl_add_u64 v[20:21], v[14:15], 0, s[84:85]
	v_lshlrev_b64 v[28:29], 1, v[30:31]
	s_add_u32 s4, s96, s84
	v_lshl_add_u64 v[20:21], v[20:21], 0, v[28:29]
	s_addc_u32 s5, s97, 0
	v_lshlrev_b64 v[12:13], 11, v[12:13]
	global_load_dwordx2 v[30:31], v[20:21], off offset:1536
	v_lshl_add_u64 v[26:27], s[4:5], 0, v[12:13]
	global_load_dwordx4 v[12:15], v[22:23], off
	global_load_dwordx4 v[116:119], v[22:23], off offset:64
	global_load_dwordx2 v[128:129], v[20:21], off offset:1568
	global_load_dwordx4 v[120:123], v[22:23], off offset:128
	global_load_dwordx2 v[130:131], v[20:21], off offset:1600
	global_load_dwordx4 v[124:127], v[22:23], off offset:192
	global_load_dwordx2 v[132:133], v[20:21], off offset:1632
	v_mul_f32_e32 v16, v16, v24
	v_mul_f32_e32 v8, v8, v24
	v_mul_f32_e32 v9, v9, v24
	v_mul_f32_e32 v10, v10, v24
	v_mul_f32_e32 v11, v11, v24
	v_mul_f32_e32 v4, v4, v24
	v_mul_f32_e32 v5, v5, v24
	v_mul_f32_e32 v6, v6, v24
	v_mul_f32_e32 v7, v7, v24
	v_mul_f32_e32 v0, v0, v24
	v_mul_f32_e32 v1, v1, v24
	v_mul_f32_e32 v2, v2, v24
	v_mul_f32_e32 v3, v3, v24
	s_add_i32 s24, s24, 1
	s_waitcnt vmcnt(7)
	v_lshlrev_b32_e32 v25, 16, v30
	v_and_b32_e32 v30, 0xffff0000, v30
	s_waitcnt vmcnt(6)
	v_mul_f32_e32 v12, v12, v16
	v_mul_f32_e32 v16, 0xbfb8aa3b, v25
	v_exp_f32_e32 v16, v16
	v_lshlrev_b32_e32 v32, 16, v31
	v_and_b32_e32 v31, 0xffff0000, v31
	v_add_f32_e32 v16, 1.0, v16
	v_div_scale_f32 v33, s[4:5], v16, v16, v25
	v_rcp_f32_e32 v34, v33
	s_nop 0
	v_fma_f32 v35, -v33, v34, 1.0
	v_fmac_f32_e32 v34, v35, v34
	v_div_scale_f32 v35, vcc, v25, v16, v25
	v_mul_f32_e32 v36, v35, v34
	v_fma_f32 v37, -v33, v36, v35
	v_fmac_f32_e32 v36, v37, v34
	v_fma_f32 v33, -v33, v36, v35
	v_div_fmas_f32 v33, v33, v34, v36
	v_div_fixup_f32 v16, v33, v16, v25
	v_mul_f32_e32 v12, v16, v12
	v_mul_f32_e32 v16, v17, v24
	v_mul_f32_e32 v13, v13, v16
	v_mul_f32_e32 v16, 0xbfb8aa3b, v30
	v_exp_f32_e32 v16, v16
	s_nop 0
	v_add_f32_e32 v16, 1.0, v16
	v_div_scale_f32 v17, s[4:5], v16, v16, v30
	v_rcp_f32_e32 v25, v17
	s_nop 0
	v_fma_f32 v33, -v17, v25, 1.0
	v_fmac_f32_e32 v25, v33, v25
	v_div_scale_f32 v33, vcc, v30, v16, v30
	v_mul_f32_e32 v34, v33, v25
	v_fma_f32 v35, -v17, v34, v33
	v_fmac_f32_e32 v34, v35, v25
	v_fma_f32 v17, -v17, v34, v33
	v_div_fmas_f32 v17, v17, v25, v34
	v_div_fixup_f32 v16, v17, v16, v30
	v_mul_f32_e32 v13, v16, v13
	v_mul_f32_e32 v16, v18, v24
	v_mul_f32_e32 v14, v14, v16
	v_mul_f32_e32 v16, 0xbfb8aa3b, v32
	v_exp_f32_e32 v16, v16
	v_cvt_pk_bf16_f32 v12, v12, v13
	s_nop 0
	v_add_f32_e32 v16, 1.0, v16
	v_div_scale_f32 v17, s[4:5], v16, v16, v32
	v_rcp_f32_e32 v18, v17
	s_nop 0
	v_fma_f32 v25, -v17, v18, 1.0
	v_fmac_f32_e32 v18, v25, v18
	v_div_scale_f32 v25, vcc, v32, v16, v32
	v_mul_f32_e32 v30, v25, v18
	v_fma_f32 v33, -v17, v30, v25
	v_fmac_f32_e32 v30, v33, v18
	v_fma_f32 v17, -v17, v30, v25
	v_div_fmas_f32 v17, v17, v18, v30
	v_div_fixup_f32 v16, v17, v16, v32
	v_mul_f32_e32 v14, v16, v14
	v_mul_f32_e32 v16, v19, v24
	v_mul_f32_e32 v15, v15, v16
	v_mul_f32_e32 v16, 0xbfb8aa3b, v31
	v_exp_f32_e32 v16, v16
	s_nop 0
	v_add_f32_e32 v16, 1.0, v16
	v_div_scale_f32 v17, s[4:5], v16, v16, v31
	v_rcp_f32_e32 v18, v17
	s_nop 0
	v_fma_f32 v19, -v17, v18, 1.0
	v_fmac_f32_e32 v18, v19, v18
	v_div_scale_f32 v19, vcc, v31, v16, v31
	v_mul_f32_e32 v25, v19, v18
	v_fma_f32 v30, -v17, v25, v19
	v_fmac_f32_e32 v25, v30, v18
	v_fma_f32 v17, -v17, v25, v19
	v_div_fmas_f32 v17, v17, v18, v25
	v_div_fixup_f32 v16, v17, v16, v31
	v_mul_f32_e32 v15, v16, v15
	v_lshl_add_u64 v[16:17], v[26:27], 0, v[28:29]
	v_cvt_pk_bf16_f32 v13, v14, v15
	global_store_dwordx2 v[16:17], v[12:13], off
	s_waitcnt vmcnt(5)
	v_mov_b32_e32 v12, v116
	v_mov_b32_e32 v13, v117
	v_mov_b32_e32 v14, v118
	v_mov_b32_e32 v15, v119
	s_nop 0
	v_mov_b32_e32 v18, v128
	v_mov_b32_e32 v19, v129
	v_mul_f32_e32 v8, v12, v8
	v_lshlrev_b32_e32 v25, 16, v18
	v_mul_f32_e32 v12, 0xbfb8aa3b, v25
	v_exp_f32_e32 v12, v12
	v_and_b32_e32 v18, 0xffff0000, v18
	v_mul_f32_e32 v9, v13, v9
	v_lshlrev_b32_e32 v26, 16, v19
	v_add_f32_e32 v12, 1.0, v12
	v_div_scale_f32 v27, s[4:5], v12, v12, v25
	v_rcp_f32_e32 v28, v27
	v_mul_f32_e32 v10, v14, v10
	v_and_b32_e32 v19, 0xffff0000, v19
	v_mul_f32_e32 v11, v15, v11
	v_fma_f32 v29, -v27, v28, 1.0
	v_fmac_f32_e32 v28, v29, v28
	v_div_scale_f32 v29, vcc, v25, v12, v25
	v_mul_f32_e32 v30, v29, v28
	v_fma_f32 v31, -v27, v30, v29
	v_fmac_f32_e32 v30, v31, v28
	v_fma_f32 v27, -v27, v30, v29
	v_div_fmas_f32 v27, v27, v28, v30
	v_div_fixup_f32 v12, v27, v12, v25
	v_mul_f32_e32 v8, v12, v8
	v_mul_f32_e32 v12, 0xbfb8aa3b, v18
	v_exp_f32_e32 v12, v12
	s_nop 0
	v_add_f32_e32 v12, 1.0, v12
	v_div_scale_f32 v13, s[4:5], v12, v12, v18
	v_rcp_f32_e32 v25, v13
	s_nop 0
	v_fma_f32 v27, -v13, v25, 1.0
	v_fmac_f32_e32 v25, v27, v25
	v_div_scale_f32 v27, vcc, v18, v12, v18
	v_mul_f32_e32 v28, v27, v25
	v_fma_f32 v29, -v13, v28, v27
	v_fmac_f32_e32 v28, v29, v25
	v_fma_f32 v13, -v13, v28, v27
	v_div_fmas_f32 v13, v13, v25, v28
	v_div_fixup_f32 v12, v13, v12, v18
	v_mul_f32_e32 v9, v12, v9
	v_mul_f32_e32 v12, 0xbfb8aa3b, v26
	v_exp_f32_e32 v12, v12
	v_cvt_pk_bf16_f32 v8, v8, v9
	s_nop 0
	v_add_f32_e32 v12, 1.0, v12
	v_div_scale_f32 v13, s[4:5], v12, v12, v26
	v_rcp_f32_e32 v14, v13
	s_nop 0
	v_fma_f32 v18, -v13, v14, 1.0
	v_fmac_f32_e32 v14, v18, v14
	v_div_scale_f32 v18, vcc, v26, v12, v26
	v_mul_f32_e32 v25, v18, v14
	v_fma_f32 v27, -v13, v25, v18
	v_fmac_f32_e32 v25, v27, v14
	v_fma_f32 v13, -v13, v25, v18
	v_div_fmas_f32 v13, v13, v14, v25
	v_div_fixup_f32 v12, v13, v12, v26
	v_mul_f32_e32 v10, v12, v10
	v_mul_f32_e32 v12, 0xbfb8aa3b, v19
	v_exp_f32_e32 v12, v12
	s_nop 0
	v_add_f32_e32 v12, 1.0, v12
	v_div_scale_f32 v13, s[4:5], v12, v12, v19
	v_rcp_f32_e32 v14, v13
	s_nop 0
	v_fma_f32 v15, -v13, v14, 1.0
	v_fmac_f32_e32 v14, v15, v14
	v_div_scale_f32 v15, vcc, v19, v12, v19
	v_mul_f32_e32 v18, v15, v14
	v_fma_f32 v25, -v13, v18, v15
	v_fmac_f32_e32 v18, v25, v14
	v_fma_f32 v13, -v13, v18, v15
	v_div_fmas_f32 v13, v13, v14, v18
	v_div_fixup_f32 v12, v13, v12, v19
	v_mul_f32_e32 v11, v12, v11
	v_cvt_pk_bf16_f32 v9, v10, v11
	global_store_dwordx2 v[16:17], v[8:9], off offset:32
	s_waitcnt vmcnt(4)
	v_mov_b32_e32 v8, v120
	v_mov_b32_e32 v9, v121
	v_mov_b32_e32 v10, v122
	v_mov_b32_e32 v11, v123
	s_nop 0
	v_mov_b32_e32 v12, v130
	v_mov_b32_e32 v13, v131
	v_mul_f32_e32 v4, v8, v4
	v_lshlrev_b32_e32 v14, 16, v12
	v_mul_f32_e32 v8, 0xbfb8aa3b, v14
	v_exp_f32_e32 v8, v8
	v_and_b32_e32 v12, 0xffff0000, v12
	v_mul_f32_e32 v5, v9, v5
	v_lshlrev_b32_e32 v15, 16, v13
	v_add_f32_e32 v8, 1.0, v8
	v_div_scale_f32 v18, s[4:5], v8, v8, v14
	v_rcp_f32_e32 v19, v18
	v_mul_f32_e32 v6, v6, v10
	v_and_b32_e32 v13, 0xffff0000, v13
	v_mul_f32_e32 v7, v7, v11
	v_fma_f32 v25, -v18, v19, 1.0
	v_fmac_f32_e32 v19, v25, v19
	v_div_scale_f32 v25, vcc, v14, v8, v14
	v_mul_f32_e32 v26, v25, v19
	v_fma_f32 v27, -v18, v26, v25
	v_fmac_f32_e32 v26, v27, v19
	v_fma_f32 v18, -v18, v26, v25
	v_div_fmas_f32 v18, v18, v19, v26
	v_div_fixup_f32 v8, v18, v8, v14
	v_mul_f32_e32 v4, v4, v8
	v_mul_f32_e32 v8, 0xbfb8aa3b, v12
	v_exp_f32_e32 v8, v8
	s_nop 0
	v_add_f32_e32 v8, 1.0, v8
	v_div_scale_f32 v9, s[4:5], v8, v8, v12
	v_rcp_f32_e32 v14, v9
	s_nop 0
	v_fma_f32 v18, -v9, v14, 1.0
	v_fmac_f32_e32 v14, v18, v14
	v_div_scale_f32 v18, vcc, v12, v8, v12
	v_mul_f32_e32 v19, v18, v14
	v_fma_f32 v25, -v9, v19, v18
	v_fmac_f32_e32 v19, v25, v14
	v_fma_f32 v9, -v9, v19, v18
	v_div_fmas_f32 v9, v9, v14, v19
	v_div_fixup_f32 v8, v9, v8, v12
	v_mul_f32_e32 v5, v5, v8
	v_mul_f32_e32 v8, 0xbfb8aa3b, v15
	v_exp_f32_e32 v8, v8
	v_cvt_pk_bf16_f32 v4, v4, v5
	s_nop 0
	v_add_f32_e32 v8, 1.0, v8
	v_div_scale_f32 v9, s[4:5], v8, v8, v15
	v_rcp_f32_e32 v10, v9
	s_nop 0
	v_fma_f32 v12, -v9, v10, 1.0
	v_fmac_f32_e32 v10, v12, v10
	v_div_scale_f32 v12, vcc, v15, v8, v15
	v_mul_f32_e32 v14, v12, v10
	v_fma_f32 v18, -v9, v14, v12
	v_fmac_f32_e32 v14, v18, v10
	v_fma_f32 v9, -v9, v14, v12
	v_div_fmas_f32 v9, v9, v10, v14
	v_div_fixup_f32 v8, v9, v8, v15
	v_mul_f32_e32 v6, v6, v8
	v_mul_f32_e32 v8, 0xbfb8aa3b, v13
	v_exp_f32_e32 v8, v8
	s_nop 0
	v_add_f32_e32 v8, 1.0, v8
	v_div_scale_f32 v9, s[4:5], v8, v8, v13
	v_rcp_f32_e32 v10, v9
	s_nop 0
	v_fma_f32 v11, -v9, v10, 1.0
	v_fmac_f32_e32 v10, v11, v10
	v_div_scale_f32 v11, vcc, v13, v8, v13
	v_mul_f32_e32 v12, v11, v10
	v_fma_f32 v14, -v9, v12, v11
	v_fmac_f32_e32 v12, v14, v10
	v_fma_f32 v9, -v9, v12, v11
	v_div_fmas_f32 v9, v9, v10, v12
	v_div_fixup_f32 v8, v9, v8, v13
	v_mul_f32_e32 v7, v7, v8
	v_cvt_pk_bf16_f32 v5, v6, v7
	global_store_dwordx2 v[16:17], v[4:5], off offset:64
	s_waitcnt vmcnt(3)
	v_mov_b32_e32 v4, v124
	v_mov_b32_e32 v5, v125
	v_mov_b32_e32 v6, v126
	v_mov_b32_e32 v7, v127
	s_nop 0
	v_mov_b32_e32 v12, v132
	v_mov_b32_e32 v13, v133
	v_mul_f32_e32 v0, v0, v4
	v_lshlrev_b32_e32 v11, 16, v12
	v_mul_f32_e32 v4, 0xbfb8aa3b, v11
	v_exp_f32_e32 v4, v4
	v_and_b32_e32 v10, 0xffff0000, v12
	v_lshlrev_b32_e32 v9, 16, v13
	v_and_b32_e32 v8, 0xffff0000, v13
	v_add_f32_e32 v4, 1.0, v4
	v_div_scale_f32 v12, s[4:5], v4, v4, v11
	v_rcp_f32_e32 v13, v12
	v_mul_f32_e32 v1, v1, v5
	v_mul_f32_e32 v2, v2, v6
	v_mul_f32_e32 v3, v3, v7
	v_fma_f32 v14, -v12, v13, 1.0
	v_fmac_f32_e32 v13, v14, v13
	v_div_scale_f32 v14, vcc, v11, v4, v11
	v_mul_f32_e32 v15, v14, v13
	v_fma_f32 v18, -v12, v15, v14
	v_fmac_f32_e32 v15, v18, v13
	v_fma_f32 v12, -v12, v15, v14
	v_div_fmas_f32 v12, v12, v13, v15
	v_div_fixup_f32 v4, v12, v4, v11
	v_mul_f32_e32 v0, v0, v4
	v_mul_f32_e32 v4, 0xbfb8aa3b, v10
	v_exp_f32_e32 v4, v4
	s_nop 0
	v_add_f32_e32 v4, 1.0, v4
	v_div_scale_f32 v5, s[4:5], v4, v4, v10
	v_rcp_f32_e32 v11, v5
	s_nop 0
	v_fma_f32 v12, -v5, v11, 1.0
	v_fmac_f32_e32 v11, v12, v11
	v_div_scale_f32 v12, vcc, v10, v4, v10
	v_mul_f32_e32 v13, v12, v11
	v_fma_f32 v14, -v5, v13, v12
	v_fmac_f32_e32 v13, v14, v11
	v_fma_f32 v5, -v5, v13, v12
	v_div_fmas_f32 v5, v5, v11, v13
	v_div_fixup_f32 v4, v5, v4, v10
	v_mul_f32_e32 v1, v1, v4
	v_mul_f32_e32 v4, 0xbfb8aa3b, v9
	v_exp_f32_e32 v4, v4
	v_cvt_pk_bf16_f32 v0, v0, v1
	s_nop 0
	v_add_f32_e32 v4, 1.0, v4
	v_div_scale_f32 v5, s[4:5], v4, v4, v9
	v_rcp_f32_e32 v6, v5
	s_nop 0
	v_fma_f32 v10, -v5, v6, 1.0
	v_fmac_f32_e32 v6, v10, v6
	v_div_scale_f32 v10, vcc, v9, v4, v9
	v_mul_f32_e32 v11, v10, v6
	v_fma_f32 v12, -v5, v11, v10
	v_fmac_f32_e32 v11, v12, v6
	v_fma_f32 v5, -v5, v11, v10
	v_div_fmas_f32 v5, v5, v6, v11
	v_div_fixup_f32 v4, v5, v4, v9
	v_mul_f32_e32 v2, v2, v4
	v_mul_f32_e32 v4, 0xbfb8aa3b, v8
	v_exp_f32_e32 v4, v4
	s_nop 0
	v_add_f32_e32 v4, 1.0, v4
	v_div_scale_f32 v5, s[4:5], v4, v4, v8
	v_rcp_f32_e32 v6, v5
	s_add_i32 s4, s12, 1
	s_cmp_eq_u32 s12, s25
	s_mov_b32 s12, s4
	v_fma_f32 v7, -v5, v6, 1.0
	v_fmac_f32_e32 v6, v7, v6
	v_div_scale_f32 v7, vcc, v8, v4, v8
	v_mul_f32_e32 v9, v7, v6
	v_fma_f32 v10, -v5, v9, v7
	v_fmac_f32_e32 v9, v10, v6
	v_fma_f32 v5, -v5, v9, v7
	v_div_fmas_f32 v5, v5, v6, v9
	v_div_fixup_f32 v4, v5, v4, v8
	v_mul_f32_e32 v3, v3, v4
	v_cvt_pk_bf16_f32 v1, v2, v3
	global_store_dwordx2 v[16:17], v[0:1], off offset:96
	s_barrier
	s_cbranch_scc1 .LBB0_119

.LBB0_135:
	s_or_b64 exec, exec, s[4:5]
	v_mul_f32_e32 v2, 0x3fb8aa3b, v17
	v_exp_f32_e32 v17, v2
	v_mul_f32_e32 v2, 0x3fb8aa3b, v18
	v_exp_f32_e32 v43, v2
	v_mul_f32_e32 v2, 0x3fb8aa3b, v19
	v_exp_f32_e32 v44, v2
	v_mul_f32_e32 v2, 0x3fb8aa3b, v21
	v_exp_f32_e32 v45, v2
	v_mul_f32_e32 v2, 0x3fb8aa3b, v22
	v_exp_f32_e32 v46, v2
	v_mul_f32_e32 v2, 0x3fb8aa3b, v23
	v_exp_f32_e32 v47, v2
	v_mul_f32_e32 v2, 0x3fb8aa3b, v25
	v_exp_f32_e32 v48, v2
	v_mul_f32_e32 v2, 0x3fb8aa3b, v28
	v_exp_f32_e32 v28, v2
	v_mul_f32_e32 v2, 0x3fb8aa3b, v33
	v_exp_f32_e32 v33, v2
	v_mul_f32_e32 v2, 0x3fb8aa3b, v35
	v_exp_f32_e32 v35, v2
	v_mul_f32_e32 v2, 0x3fb8aa3b, v37
	v_exp_f32_e32 v37, v2
	v_mul_f32_e32 v2, 0x3fb8aa3b, v39
	v_exp_f32_e32 v24, v2
	v_mul_f32_e32 v2, 0x3fb8aa3b, v40
	v_exp_f32_e32 v23, v2
	v_mul_f32_e32 v2, 0x3fb8aa3b, v41
	v_exp_f32_e32 v19, v2
	v_mul_f32_e32 v2, 0x3fb8aa3b, v42
	v_exp_f32_e32 v18, v2
	v_mul_f32_e32 v2, 0x3fb8aa3b, v5
	v_add_f32_e32 v5, 1.0, v17
	v_div_scale_f32 v17, s[4:5], v5, v5, 1.0
	v_rcp_f32_e32 v21, v17
	v_add_f32_e32 v28, 1.0, v28
	v_add_f32_e32 v33, 1.0, v33
	v_add_f32_e32 v24, 1.0, v24
	v_fma_f32 v22, -v17, v21, 1.0
	v_fmac_f32_e32 v21, v22, v21
	v_div_scale_f32 v22, vcc, 1.0, v5, 1.0
	v_mul_f32_e32 v25, v22, v21
	v_fma_f32 v39, -v17, v25, v22
	v_fmac_f32_e32 v25, v39, v21
	v_fma_f32 v17, -v17, v25, v22
	v_div_fmas_f32 v17, v17, v21, v25
	v_div_fixup_f32 v5, v17, v5, 1.0
	v_add_f32_e32 v17, 1.0, v43
	v_div_scale_f32 v21, s[4:5], v17, v17, 1.0
	v_rcp_f32_e32 v22, v21
	v_add_f32_e32 v23, 1.0, v23
	v_add_f32_e32 v19, 1.0, v19
	v_add_f32_e32 v18, 1.0, v18
	v_fma_f32 v25, -v21, v22, 1.0
	v_fmac_f32_e32 v22, v25, v22
	v_div_scale_f32 v25, vcc, 1.0, v17, 1.0
	v_mul_f32_e32 v39, v25, v22
	v_fma_f32 v40, -v21, v39, v25
	v_fmac_f32_e32 v39, v40, v22
	v_fma_f32 v21, -v21, v39, v25
	v_div_fmas_f32 v21, v21, v22, v39
	v_div_fixup_f32 v17, v21, v17, 1.0
	v_add_f32_e32 v21, 1.0, v44
	v_div_scale_f32 v22, s[4:5], v21, v21, 1.0
	v_rcp_f32_e32 v25, v22
	v_exp_f32_e32 v2, v2
	v_mul_f32_e32 v5, v9, v5
	v_mul_f32_e32 v17, v9, v17
	v_fma_f32 v39, -v22, v25, 1.0
	v_fmac_f32_e32 v25, v39, v25
	v_div_scale_f32 v39, vcc, 1.0, v21, 1.0
	v_mul_f32_e32 v40, v39, v25
	v_fma_f32 v41, -v22, v40, v39
	v_fmac_f32_e32 v40, v41, v25
	v_fma_f32 v22, -v22, v40, v39
	v_div_fmas_f32 v22, v22, v25, v40
	v_div_fixup_f32 v21, v22, v21, 1.0
	v_add_f32_e32 v22, 1.0, v45
	v_div_scale_f32 v25, s[4:5], v22, v22, 1.0
	v_rcp_f32_e32 v39, v25
	v_add_f32_e32 v2, 1.0, v2
	v_mul_f32_e32 v21, v9, v21
	v_fma_f32 v40, -v25, v39, 1.0
	v_fmac_f32_e32 v39, v40, v39
	v_div_scale_f32 v40, vcc, 1.0, v22, 1.0
	v_mul_f32_e32 v41, v40, v39
	v_fma_f32 v42, -v25, v41, v40
	v_fmac_f32_e32 v41, v42, v39
	v_fma_f32 v25, -v25, v41, v40
	v_div_fmas_f32 v25, v25, v39, v41
	v_div_fixup_f32 v22, v25, v22, 1.0
	v_add_f32_e32 v25, 1.0, v46
	v_div_scale_f32 v39, s[4:5], v25, v25, 1.0
	v_rcp_f32_e32 v40, v39
	v_mul_f32_e32 v22, v9, v22
	v_fma_f32 v41, -v39, v40, 1.0
	v_fmac_f32_e32 v40, v41, v40
	v_div_scale_f32 v41, vcc, 1.0, v25, 1.0
	v_mul_f32_e32 v42, v41, v40
	v_fma_f32 v43, -v39, v42, v41
	v_fmac_f32_e32 v42, v43, v40
	v_fma_f32 v39, -v39, v42, v41
	v_div_fmas_f32 v39, v39, v40, v42
	v_div_fixup_f32 v25, v39, v25, 1.0
	v_add_f32_e32 v39, 1.0, v47
	v_div_scale_f32 v40, s[4:5], v39, v39, 1.0
	v_rcp_f32_e32 v41, v40
	v_mul_f32_e32 v25, v9, v25
	v_fma_f32 v42, -v40, v41, 1.0
	v_fmac_f32_e32 v41, v42, v41
	v_div_scale_f32 v42, vcc, 1.0, v39, 1.0
	v_mul_f32_e32 v43, v42, v41
	v_fma_f32 v44, -v40, v43, v42
	v_fmac_f32_e32 v43, v44, v41
	v_fma_f32 v40, -v40, v43, v42
	v_div_fmas_f32 v40, v40, v41, v43
	v_div_fixup_f32 v39, v40, v39, 1.0
	v_add_f32_e32 v40, 1.0, v48
	v_div_scale_f32 v41, s[4:5], v40, v40, 1.0
	v_rcp_f32_e32 v42, v41
	v_mul_f32_e32 v39, v9, v39
	v_fma_f32 v43, -v41, v42, 1.0
	v_fmac_f32_e32 v42, v43, v42
	v_div_scale_f32 v43, vcc, 1.0, v40, 1.0
	v_mul_f32_e32 v44, v43, v42
	v_fma_f32 v45, -v41, v44, v43
	v_fmac_f32_e32 v44, v45, v42
	v_fma_f32 v41, -v41, v44, v43
	v_div_fmas_f32 v41, v41, v42, v44
	v_div_fixup_f32 v40, v41, v40, 1.0
	v_div_scale_f32 v41, s[4:5], v28, v28, 1.0
	v_rcp_f32_e32 v42, v41
	v_mul_f32_e32 v40, v9, v40
	v_fma_f32 v43, -v41, v42, 1.0
	v_fmac_f32_e32 v42, v43, v42
	v_div_scale_f32 v43, vcc, 1.0, v28, 1.0
	v_mul_f32_e32 v44, v43, v42
	v_fma_f32 v45, -v41, v44, v43
	v_fmac_f32_e32 v44, v45, v42
	v_fma_f32 v41, -v41, v44, v43
	v_div_fmas_f32 v41, v41, v42, v44
	v_div_fixup_f32 v28, v41, v28, 1.0
	v_div_scale_f32 v41, s[4:5], v33, v33, 1.0
	v_rcp_f32_e32 v42, v41
	v_mul_f32_e32 v28, v9, v28
	v_fma_f32 v43, -v41, v42, 1.0
	v_fmac_f32_e32 v42, v43, v42
	v_div_scale_f32 v43, vcc, 1.0, v33, 1.0
	v_mul_f32_e32 v44, v43, v42
	v_fma_f32 v45, -v41, v44, v43
	v_fmac_f32_e32 v44, v45, v42
	v_fma_f32 v41, -v41, v44, v43
	v_div_fmas_f32 v41, v41, v42, v44
	v_div_fixup_f32 v33, v41, v33, 1.0
	v_mul_f32_e32 v41, v9, v33
	v_add_f32_e32 v33, 1.0, v35
	v_div_scale_f32 v35, s[4:5], v33, v33, 1.0
	v_rcp_f32_e32 v42, v35
	s_nop 0
	v_fma_f32 v43, -v35, v42, 1.0
	v_fmac_f32_e32 v42, v43, v42
	v_div_scale_f32 v43, vcc, 1.0, v33, 1.0
	v_mul_f32_e32 v44, v43, v42
	v_fma_f32 v45, -v35, v44, v43
	v_fmac_f32_e32 v44, v45, v42
	v_fma_f32 v35, -v35, v44, v43
	v_div_fmas_f32 v35, v35, v42, v44
	v_div_fixup_f32 v33, v35, v33, 1.0
	v_mul_f32_e32 v42, v9, v33
	v_add_f32_e32 v33, 1.0, v37
	v_div_scale_f32 v35, s[4:5], v33, v33, 1.0
	v_rcp_f32_e32 v37, v35
	s_nop 0
	v_fma_f32 v43, -v35, v37, 1.0
	v_fmac_f32_e32 v37, v43, v37
	v_div_scale_f32 v43, vcc, 1.0, v33, 1.0
	v_mul_f32_e32 v44, v43, v37
	v_fma_f32 v45, -v35, v44, v43
	v_fmac_f32_e32 v44, v45, v37
	v_fma_f32 v35, -v35, v44, v43
	v_div_fmas_f32 v35, v35, v37, v44
	v_div_fixup_f32 v33, v35, v33, 1.0
	v_mul_f32_e32 v37, v9, v33
	v_div_scale_f32 v33, s[4:5], v24, v24, 1.0
	v_rcp_f32_e32 v35, v33
	s_nop 0
	v_fma_f32 v43, -v33, v35, 1.0
	v_fmac_f32_e32 v35, v43, v35
	v_div_scale_f32 v43, vcc, 1.0, v24, 1.0
	v_mul_f32_e32 v44, v43, v35
	v_fma_f32 v45, -v33, v44, v43
	v_fmac_f32_e32 v44, v45, v35
	v_fma_f32 v33, -v33, v44, v43
	v_div_fmas_f32 v33, v33, v35, v44
	v_div_fixup_f32 v24, v33, v24, 1.0
	v_div_scale_f32 v33, s[4:5], v23, v23, 1.0
	v_rcp_f32_e32 v35, v33
	v_mul_f32_e32 v24, v9, v24
	v_fma_f32 v43, -v33, v35, 1.0
	v_fmac_f32_e32 v35, v43, v35
	v_div_scale_f32 v43, vcc, 1.0, v23, 1.0
	v_mul_f32_e32 v44, v43, v35
	v_fma_f32 v45, -v33, v44, v43
	v_fmac_f32_e32 v44, v45, v35
	v_fma_f32 v33, -v33, v44, v43
	v_div_fmas_f32 v33, v33, v35, v44
	v_div_fixup_f32 v23, v33, v23, 1.0
	v_div_scale_f32 v33, s[4:5], v19, v19, 1.0
	v_rcp_f32_e32 v35, v33
	v_mul_f32_e32 v23, v9, v23
	v_fma_f32 v43, -v33, v35, 1.0
	v_fmac_f32_e32 v35, v43, v35
	v_div_scale_f32 v43, vcc, 1.0, v19, 1.0
	v_mul_f32_e32 v44, v43, v35
	v_fma_f32 v45, -v33, v44, v43
	v_fmac_f32_e32 v44, v45, v35
	v_fma_f32 v33, -v33, v44, v43
	v_div_fmas_f32 v33, v33, v35, v44
	v_div_fixup_f32 v19, v33, v19, 1.0
	v_mul_f32_e32 v43, v9, v19
	v_div_scale_f32 v19, s[4:5], v18, v18, 1.0
	v_rcp_f32_e32 v33, v19
	s_nop 0
	v_fma_f32 v35, -v19, v33, 1.0
	v_fmac_f32_e32 v33, v35, v33
	v_div_scale_f32 v35, vcc, 1.0, v18, 1.0
	v_mul_f32_e32 v44, v35, v33
	v_fma_f32 v45, -v19, v44, v35
	v_fmac_f32_e32 v44, v45, v33
	v_fma_f32 v19, -v19, v44, v35
	v_div_fmas_f32 v19, v19, v33, v44
	v_div_fixup_f32 v18, v19, v18, 1.0
	v_mul_f32_e32 v44, v9, v18
	v_div_scale_f32 v18, s[4:5], v2, v2, 1.0
	v_rcp_f32_e32 v19, v18
	s_nop 0
	v_fma_f32 v33, -v18, v19, 1.0
	v_fmac_f32_e32 v19, v33, v19
	v_div_scale_f32 v33, vcc, 1.0, v2, 1.0
	v_mul_f32_e32 v35, v33, v19
	v_fma_f32 v45, -v18, v35, v33
	v_fmac_f32_e32 v35, v45, v19
	v_fma_f32 v18, -v18, v35, v33
	v_div_fmas_f32 v18, v18, v19, v35
	v_div_fixup_f32 v2, v18, v2, 1.0
	v_lshrrev_b32_e32 v35, 4, v7
	v_add_f32_e32 v7, v10, v1
	v_mad_u64_u32 v[18:19], s[4:5], v29, s80, v[0:1]
	ds_write2st64_b32 v18, v7, v5 offset1:65
	v_add_f32_e32 v5, v11, v1
	v_mad_u64_u32 v[10:11], s[4:5], v12, s81, v[0:1]
	v_add_f32_e32 v0, v3, v1
	ds_write2_b32 v10, v5, v0 offset1:65
	v_add_u32_e32 v0, 0x4000, v10
	ds_write2_b32 v0, v17, v21 offset0:64 offset1:129
	v_add_f32_e32 v0, v13, v1
	v_add_f32_e32 v3, v14, v1
	ds_write2_b32 v10, v0, v3 offset0:130 offset1:195
	v_add_u32_e32 v0, 0x4200, v10
	ds_write2_b32 v0, v22, v25 offset0:66 offset1:131
	v_add_f32_e32 v0, v15, v1
	v_add_f32_e32 v3, v16, v1
	v_add_u32_e32 v5, 0x400, v10
	ds_write2_b32 v5, v0, v3 offset0:4 offset1:69
	v_add_u32_e32 v0, 0x4400, v10
	ds_write2_b32 v0, v39, v40 offset0:68 offset1:133
	v_add_f32_e32 v0, v20, v1
	v_add_f32_e32 v3, v26, v1
	ds_write2_b32 v5, v0, v3 offset0:134 offset1:199
	v_add_u32_e32 v0, 0x4600, v10
	ds_write2_b32 v0, v28, v41 offset0:70 offset1:135
	v_add_f32_e32 v0, v27, v1
	v_add_f32_e32 v3, v30, v1
	v_add_u32_e32 v5, 0x800, v10
	ds_write_b32 v10, v42 offset:18720
	ds_write2_b32 v5, v0, v3 offset0:8 offset1:73
	v_add_u32_e32 v3, 0x4800, v10
	v_add_f32_e32 v0, v31, v1
	ds_write2_b32 v3, v37, v24 offset0:137 offset1:202
	v_add_f32_e32 v3, v34, v1
	v_and_b32_e32 v33, 15, v32
	ds_write2_b32 v5, v0, v3 offset0:138 offset1:203
	v_add_f32_e32 v0, v36, v1
	v_add_u32_e32 v3, 0x4c00, v10
	v_add_f32_e32 v5, v38, v1
	v_add_u32_e32 v7, 0xc00, v10
	ds_write2_b32 v3, v23, v43 offset0:11 offset1:76
	ds_write2_b32 v7, v0, v5 offset0:12 offset1:77
	v_add_f32_e32 v0, v4, v1
	v_or_b32_e32 v28, v6, v33
	v_mul_f32_e32 v2, v9, v2
	ds_write_b32 v10, v0 offset:3640
	ds_write2_b32 v3, v44, v2 offset0:141 offset1:206
	v_lshlrev_b32_e32 v30, 3, v35
	v_lshl_add_u32 v0, v28, 6, v28
	v_add_lshl_u32 v16, v0, v30, 2
	s_waitcnt lgkmcnt(0)
	s_barrier
	ds_read2st64_b32 v[0:1], v16 offset1:130
	v_add_u32_e32 v20, 0xfffffefc, v8
	v_cmp_lt_u32_e64 s[4:5], 63, v32
	v_mov_b32_e32 v18, 0
	v_lshl_add_u32 v48, v30, 2, v20
	v_mov_b32_e32 v17, 0
	s_and_saveexec_b64 s[16:17], s[4:5]
	ds_read_b32 v17, v48
	s_or_b64 exec, exec, s[16:17]
	v_add_u32_e32 v2, 4, v16
	ds_read2st64_b32 v[2:3], v2 offset1:130
	v_or_b32_e32 v4, 1, v30
	v_lshl_add_u32 v49, v4, 2, v20
	s_and_saveexec_b64 s[16:17], s[4:5]
	ds_read_b32 v18, v49
	s_or_b64 exec, exec, s[16:17]
	v_add_u32_e32 v4, 8, v16
	ds_read2st64_b32 v[4:5], v4 offset1:130
	v_or_b32_e32 v6, 2, v30
	v_mov_b32_e32 v21, 0
	v_lshl_add_u32 v50, v6, 2, v20
	v_mov_b32_e32 v19, 0
	s_and_saveexec_b64 s[16:17], s[4:5]
	ds_read_b32 v19, v50
	s_or_b64 exec, exec, s[16:17]
	v_add_u32_e32 v6, 12, v16
	ds_read2st64_b32 v[6:7], v6 offset1:130
	v_or_b32_e32 v8, 3, v30
	v_lshl_add_u32 v51, v8, 2, v20
	s_and_saveexec_b64 s[16:17], s[4:5]
	ds_read_b32 v21, v51
	s_or_b64 exec, exec, s[16:17]
	v_add_u32_e32 v8, 16, v16
	ds_read2st64_b32 v[8:9], v8 offset1:130
	v_or_b32_e32 v10, 4, v30
	v_mov_b32_e32 v24, 0
	v_lshl_add_u32 v52, v10, 2, v20
	v_mov_b32_e32 v22, 0
	s_and_saveexec_b64 s[16:17], s[4:5]
	ds_read_b32 v22, v52
	s_or_b64 exec, exec, s[16:17]
	v_add_u32_e32 v10, 20, v16
	ds_read2st64_b32 v[12:13], v10 offset1:130
	v_or_b32_e32 v10, 5, v30
	v_lshl_add_u32 v53, v10, 2, v20
	s_and_saveexec_b64 s[16:17], s[4:5]
	ds_read_b32 v24, v53
	s_or_b64 exec, exec, s[16:17]
	v_add_u32_e32 v10, 24, v16
	ds_read2st64_b32 v[14:15], v10 offset1:130
	v_or_b32_e32 v10, 6, v30
	v_mov_b32_e32 v23, 0
	v_lshl_add_u32 v54, v10, 2, v20
	v_mov_b32_e32 v25, 0
	s_and_saveexec_b64 s[16:17], s[4:5]
	ds_read_b32 v25, v54
	s_or_b64 exec, exec, s[16:17]
	v_add_u32_e32 v10, 28, v16
	ds_read2st64_b32 v[10:11], v10 offset1:130
	v_or_b32_e32 v26, 7, v30
	v_lshl_add_u32 v55, v26, 2, v20
	s_and_saveexec_b64 s[16:17], s[4:5]
	ds_read_b32 v23, v55
	s_or_b64 exec, exec, s[16:17]
	s_waitcnt lgkmcnt(2)
	v_sub_f32_e32 v24, v12, v24
	s_waitcnt lgkmcnt(1)
	v_sub_f32_e32 v25, v14, v25
	v_exp_f32_e32 v14, v14
	v_exp_f32_e32 v24, v24
	v_exp_f32_e32 v12, v12
	v_exp_f32_e32 v25, v25
	v_mul_f32_e32 v27, v15, v14
	v_mul_f32_e32 v14, v13, v24
	v_mul_f32_e32 v26, v13, v12
	v_sub_f32_e32 v12, v8, v22
	v_sub_f32_e32 v13, v6, v21
	v_exp_f32_e32 v12, v12
	v_exp_f32_e32 v8, v8
	v_exp_f32_e32 v13, v13
	v_exp_f32_e32 v6, v6
	v_mul_f32_e32 v25, v15, v25
	v_mul_f32_e32 v15, v9, v12
	v_mul_f32_e32 v8, v9, v8
	v_mul_f32_e32 v9, v7, v13
	v_mul_f32_e32 v6, v7, v6
	v_sub_f32_e32 v7, v4, v19
	v_sub_f32_e32 v12, v2, v18
	v_exp_f32_e32 v7, v7
	v_exp_f32_e32 v4, v4
	v_exp_f32_e32 v12, v12
	v_exp_f32_e32 v2, v2
	v_mul_f32_e32 v7, v5, v7
	v_mul_f32_e32 v4, v5, v4
	v_mul_f32_e32 v5, v3, v12
	v_mul_f32_e32 v2, v3, v2
	v_sub_f32_e32 v3, v0, v17
	v_exp_f32_e32 v0, v0
	s_waitcnt lgkmcnt(0)
	v_sub_f32_e32 v12, v10, v23
	v_exp_f32_e32 v3, v3
	v_exp_f32_e32 v12, v12
	v_mul_f32_e32 v0, v1, v0
	v_cvt_pk_bf16_f32 v24, v0, v2
	v_mul_f32_e32 v3, v1, v3
	v_mul_f32_e32 v1, v11, v12
	v_add_u32_e32 v0, 0x80, v16
	v_cvt_pk_bf16_f32 v14, v15, v14
	v_cvt_pk_bf16_f32 v15, v25, v1
	ds_read2st64_b32 v[0:1], v0 offset1:130
	v_exp_f32_e32 v10, v10
	v_or_b32_e32 v2, 32, v30
	v_mov_b32_e32 v22, 0
	v_lshl_add_u32 v56, v2, 2, v20
	v_mov_b32_e32 v21, 0
	v_mul_f32_e32 v10, v11, v10
	v_cvt_pk_bf16_f32 v12, v3, v5
	v_cvt_pk_bf16_f32 v13, v7, v9
	v_cvt_pk_bf16_f32 v25, v4, v6
	v_cvt_pk_bf16_f32 v26, v8, v26
	v_cvt_pk_bf16_f32 v27, v27, v10
	s_and_saveexec_b64 s[16:17], s[4:5]
	ds_read_b32 v21, v56
	s_or_b64 exec, exec, s[16:17]
	v_add_u32_e32 v2, 0x84, v16
	ds_read2st64_b32 v[2:3], v2 offset1:130
	v_or_b32_e32 v4, 33, v30
	v_lshl_add_u32 v57, v4, 2, v20
	s_and_saveexec_b64 s[16:17], s[4:5]
	ds_read_b32 v22, v57
	s_or_b64 exec, exec, s[16:17]
	v_add_u32_e32 v4, 0x88, v16
	ds_read2st64_b32 v[4:5], v4 offset1:130
	v_or_b32_e32 v6, 34, v30
	v_mov_b32_e32 v31, 0
	v_lshl_add_u32 v58, v6, 2, v20
	v_mov_b32_e32 v23, 0
	s_and_saveexec_b64 s[16:17], s[4:5]
	ds_read_b32 v23, v58
	s_or_b64 exec, exec, s[16:17]
	v_add_u32_e32 v6, 0x8c, v16
	ds_read2st64_b32 v[6:7], v6 offset1:130
	v_or_b32_e32 v8, 35, v30
	v_lshl_add_u32 v59, v8, 2, v20
	s_and_saveexec_b64 s[16:17], s[4:5]
	ds_read_b32 v31, v59
	s_or_b64 exec, exec, s[16:17]
	v_add_u32_e32 v8, 0x90, v16
	ds_read2st64_b32 v[8:9], v8 offset1:130
	v_or_b32_e32 v10, 36, v30
	v_mov_b32_e32 v36, 0
	v_lshl_add_u32 v60, v10, 2, v20
	v_mov_b32_e32 v34, 0
	s_and_saveexec_b64 s[16:17], s[4:5]
	ds_read_b32 v34, v60
	s_or_b64 exec, exec, s[16:17]
	v_add_u32_e32 v10, 0x94, v16
	ds_read2st64_b32 v[10:11], v10 offset1:130
	v_or_b32_e32 v17, 37, v30
	v_lshl_add_u32 v61, v17, 2, v20
	s_and_saveexec_b64 s[16:17], s[4:5]
	ds_read_b32 v36, v61
	s_or_b64 exec, exec, s[16:17]
	v_add_u32_e32 v17, 0x98, v16
	ds_read2st64_b32 v[18:19], v17 offset1:130
	v_or_b32_e32 v17, 38, v30
	v_mov_b32_e32 v37, 0
	v_lshl_add_u32 v62, v17, 2, v20
	v_mov_b32_e32 v38, 0
	s_and_saveexec_b64 s[16:17], s[4:5]
	ds_read_b32 v38, v62
	s_or_b64 exec, exec, s[16:17]
	v_add_u32_e32 v16, 0x9c, v16
	ds_read2st64_b32 v[16:17], v16 offset1:130
	v_or_b32_e32 v39, 39, v30
	v_lshl_add_u32 v63, v39, 2, v20
	s_and_saveexec_b64 s[16:17], s[4:5]
	ds_read_b32 v37, v63
	s_or_b64 exec, exec, s[16:17]
	s_waitcnt lgkmcnt(1)
	v_sub_f32_e32 v20, v18, v38
	v_exp_f32_e32 v20, v20
	v_exp_f32_e32 v18, v18
	s_ashr_i32 s13, s12, 31
	s_lshl_b64 s[16:17], s[12:13], 13
	v_mul_f32_e32 v38, v19, v20
	v_mul_f32_e32 v18, v19, v18
	v_sub_f32_e32 v19, v10, v36
	v_exp_f32_e32 v19, v19
	v_exp_f32_e32 v10, v10
	s_add_u32 s16, s66, s16
	s_addc_u32 s17, s70, s17
	v_mul_f32_e32 v19, v11, v19
	v_mul_f32_e32 v10, v11, v10
	v_sub_f32_e32 v11, v8, v34
	v_exp_f32_e32 v11, v11
	v_exp_f32_e32 v8, v8
	v_lshlrev_b32_e32 v152, 1, v30
	v_mul_f32_e32 v11, v9, v11
	v_mul_f32_e32 v8, v9, v8
	v_sub_f32_e32 v9, v6, v31
	v_exp_f32_e32 v9, v9
	v_exp_f32_e32 v6, v6
	v_mul_f32_e32 v9, v7, v9
	v_mul_f32_e32 v6, v7, v6
	v_sub_f32_e32 v7, v4, v23
	v_exp_f32_e32 v7, v7
	v_exp_f32_e32 v4, v4
	v_mul_f32_e32 v7, v5, v7
	v_mul_f32_e32 v4, v5, v4
	v_sub_f32_e32 v5, v2, v22
	v_exp_f32_e32 v5, v5
	v_exp_f32_e32 v2, v2
	v_cvt_pk_bf16_f32 v22, v11, v19
	v_mul_f32_e32 v5, v3, v5
	v_mul_f32_e32 v2, v3, v2
	v_sub_f32_e32 v3, v0, v21
	v_exp_f32_e32 v3, v3
	v_exp_f32_e32 v0, v0
	v_cvt_pk_bf16_f32 v21, v7, v9
	v_mul_f32_e32 v3, v1, v3
	v_mul_f32_e32 v0, v1, v0
	s_waitcnt lgkmcnt(0)
	v_sub_f32_e32 v1, v16, v37
	v_exp_f32_e32 v1, v1
	v_cvt_pk_bf16_f32 v20, v3, v5
	v_cvt_pk_bf16_f32 v0, v0, v2
	v_cvt_pk_bf16_f32 v2, v8, v10
	v_exp_f32_e32 v16, v16
	v_mul_f32_e32 v1, v17, v1
	v_cvt_pk_bf16_f32 v23, v38, v1
	v_cvt_pk_bf16_f32 v1, v4, v6
	v_lshl_add_u64 v[4:5], s[16:17], 0, v[152:153]
	v_lshlrev_b32_e32 v152, 7, v33
	v_lshl_add_u64 v[30:31], v[4:5], 0, v[152:153]
	global_load_dwordx4 v[116:119], v[30:31], off
	global_load_dwordx4 v[120:123], v[30:31], off offset:64
	global_load_dwordx4 v[124:127], v[30:31], off offset:2048
	global_load_dwordx4 v[128:131], v[30:31], off offset:2112
	v_add_co_u32_e32 v30, vcc, s64, v30
	s_nop 1
	v_addc_co_u32_e32 v31, vcc, 0, v31, vcc
	global_load_dwordx4 v[132:135], v[30:31], off
	global_load_dwordx4 v[136:139], v[30:31], off offset:64
	global_load_dwordx4 v[140:143], v[30:31], off offset:2048
	global_load_dwordx4 v[144:147], v[30:31], off offset:2112
	v_mul_f32_e32 v16, v17, v16
	v_cvt_pk_bf16_f32 v3, v18, v16
	v_lshlrev_b32_e32 v152, 2, v35
	s_waitcnt vmcnt(6)
	v_mfma_f32_16x16x32_bf16 v[16:19], v[116:119], v[24:27], 0
	v_mfma_f32_16x16x32_bf16 v[16:19], v[120:123], v[0:3], v[16:19]
	s_waitcnt vmcnt(4)
	v_mfma_f32_16x16x32_bf16 v[8:11], v[124:127], v[24:27], 0
	v_mfma_f32_16x16x32_bf16 v[8:11], v[128:131], v[0:3], v[8:11]
	s_waitcnt vmcnt(2)
	v_mfma_f32_16x16x32_bf16 v[4:7], v[132:135], v[24:27], 0
	v_mfma_f32_16x16x32_bf16 v[4:7], v[136:139], v[0:3], v[4:7]
	s_waitcnt vmcnt(0)
	v_mfma_f32_16x16x32_bf16 v[24:27], v[140:143], v[24:27], 0
	v_mfma_f32_16x16x32_bf16 v[0:3], v[144:147], v[0:3], v[24:27]
	s_nop 4
	v_ashrrev_i32_e32 v24, 7, v32
	v_cmp_lt_i32_e32 vcc, -1, v24
	s_and_saveexec_b64 s[16:17], vcc
	s_xor_b64 s[16:17], exec, s[16:17]
	s_cbranch_execz .LBB0_242
	s_lshr_b32 s13, s12, 6
	s_and_b32 s13, s13, 3
	s_lshl_b32 s13, s13, 3
	s_add_i32 s18, s14, s13
	s_ashr_i32 s19, s18, 31
	s_and_b32 s15, s24, 63
	v_add_u32_e32 v64, 1, v24
	v_lshlrev_b32_e32 v24, 5, v35
	s_lshl_b64 s[18:19], s[18:19], 19
	v_and_b32_e32 v25, 48, v32
	s_lshl_b32 s15, s15, 7
	v_mad_u32_u24 v65, v33, s81, v24
	v_lshl_or_b32 v24, v33, 13, s18
	v_lshrrev_b32_e32 v25, 1, v25
	v_or3_b32 v24, v24, s15, v25
	v_mov_b32_e32 v25, s19
	v_mov_b64_e32 v[30:31], v[152:153]
	v_lshl_add_u64 v[32:33], s[0:1], 0, v[24:25]
	s_mov_b32 s13, 0
	s_mov_b64 s[18:19], 0
	s_branch .LBB0_171

.LBB0_170:
	s_or_b64 exec, exec, s[20:21]
	v_cvt_pk_bf16_f32 v36, v25, v24
	v_cvt_pk_bf16_f32 v37, v26, v27
	v_add_co_u32_e32 v116, vcc, 0x20000, v32
	s_nop 1
	v_addc_co_u32_e32 v117, vcc, 0, v33, vcc
	v_add_co_u32_e32 v118, vcc, 0x40000, v32
	s_nop 1
	v_addc_co_u32_e32 v119, vcc, 0, v33, vcc
	v_add_co_u32_e32 v120, vcc, 0x60000, v32
	s_nop 1
	v_addc_co_u32_e32 v121, vcc, 0, v33, vcc
	global_load_dwordx2 v[132:133], v[32:33], off
	global_load_dwordx2 v[134:135], v[32:33], off offset:32
	global_load_dwordx2 v[136:137], v[116:117], off
	global_load_dwordx2 v[138:139], v[116:117], off offset:32
	global_load_dwordx2 v[140:141], v[118:119], off
	global_load_dwordx2 v[142:143], v[118:119], off offset:32
	global_load_dwordx2 v[144:145], v[120:121], off
	global_load_dwordx2 v[146:147], v[120:121], off offset:32
	v_cvt_pk_bf16_f32 v34, v67, v66
	v_cvt_pk_bf16_f32 v35, v68, v69
	v_add_u32_e32 v64, -1, v64
	s_add_i32 s13, s13, 2
	v_add_u32_e32 v152, 32, v152
	v_add_u32_e32 v65, 0x2080, v65
	v_cmp_eq_u32_e32 vcc, 0, v64
	v_lshl_add_u64 v[32:33], v[32:33], 0, 64
	s_or_b64 s[18:19], vcc, s[18:19]
	s_waitcnt vmcnt(6)
	v_mfma_f32_16x16x32_bf16 v[16:19], v[132:135], v[34:37], v[16:19]
	s_waitcnt vmcnt(4)
	v_mfma_f32_16x16x32_bf16 v[8:11], v[136:139], v[34:37], v[8:11]
	s_waitcnt vmcnt(2)
	v_mfma_f32_16x16x32_bf16 v[4:7], v[140:143], v[34:37], v[4:7]
	s_waitcnt vmcnt(0)
	v_mfma_f32_16x16x32_bf16 v[0:3], v[144:147], v[34:37], v[0:3]
	s_andn2_b64 exec, exec, s[18:19]
	s_cbranch_execz .LBB0_241

.LBB0_266:
	s_or_b64 exec, exec, s[12:13]
	s_lshl_b32 s12, s21, 21
	s_lshl_b32 s13, s23, 18
	s_add_i32 s12, s12, s13
	s_lshl_b32 s12, s12, 1
	v_and_b32_e32 v22, 15, v3
	s_add_u32 s12, s0, s12
	s_addc_u32 s13, s1, 0
	s_lshl_b32 s21, s22, 1
	v_or_b32_e32 v0, v5, v22
	s_add_u32 s12, s12, s21
	v_ashrrev_i32_e32 v1, 31, v0
	s_addc_u32 s13, s13, 0
	v_lshlrev_b64 v[0:1], 13, v[0:1]
	v_lshl_add_u64 v[0:1], s[12:13], 0, v[0:1]
	v_and_b32_e32 v152, 48, v2
	v_lshl_add_u64 v[0:1], v[0:1], 0, v[152:153]
	global_load_dwordx4 v[116:119], v[0:1], off
	global_load_dwordx4 v[120:123], v[0:1], off offset:64
	s_waitcnt lgkmcnt(0)
	s_barrier
	v_and_b32_e32 v0, 48, v3
	s_movk_i32 s12, 0x90
	v_mad_u32_u24 v5, v22, s12, v0
	ds_read_b128 v[14:17], v5 offset:1024
	ds_read_b128 v[18:21], v5 offset:1088
	v_lshlrev_b32_e32 v0, 4, v2
	v_lshlrev_b32_e32 v1, 10, v4
	s_movk_i32 s12, 0x300
	v_and_or_b32 v4, v0, s12, v1
	v_or_b32_e32 v0, v4, v22
	s_add_u32 s12, s18, s4
	v_ashrrev_i32_e32 v1, 31, v0
	s_addc_u32 s13, s19, s5
	v_lshl_add_u64 v[2:3], v[0:1], 2, s[12:13]
	s_mov_b32 s21, 0x3950000
	v_add_co_u32_e32 v2, vcc, s21, v2
	v_ashrrev_i32_e32 v1, 31, v4
	s_nop 0
	v_addc_co_u32_e32 v3, vcc, 0, v3, vcc
	v_lshl_add_u64 v[0:1], v[0:1], 2, s[12:13]
	s_add_i32 s15, s15, 1
	s_add_u32 s4, s4, 0x4000
	s_addc_u32 s5, s5, 0
	s_add_i32 s20, s20, 64
	s_cmpk_eq_u32 s4, 0x8000
	s_waitcnt vmcnt(1) lgkmcnt(1)
	v_mfma_f32_16x16x32_bf16 v[14:17], v[116:119], v[14:17], 0
	s_waitcnt vmcnt(0) lgkmcnt(0)
	v_mfma_f32_16x16x32_bf16 v[14:17], v[120:123], v[18:21], v[14:17]
	v_add_co_u32_e32 v18, vcc, s21, v0
	s_nop 1
	v_addc_co_u32_e32 v19, vcc, 0, v1, vcc
	s_nop 3
	global_store_dword v[2:3], v14, off offset:2304
	global_store_dword v[18:19], v15, off offset:2560
	global_store_dword v[18:19], v16, off offset:2816
	global_store_dword v[18:19], v17, off offset:3072
	ds_read_b128 v[0:3], v5 offset:3328
	ds_read_b128 v[14:17], v5 offset:3392
	s_waitcnt lgkmcnt(1)
	v_mfma_f32_16x16x32_bf16 v[0:3], v[116:119], v[0:3], 0
	s_waitcnt lgkmcnt(0)
	v_mfma_f32_16x16x32_bf16 v[0:3], v[120:123], v[14:17], v[0:3]
	s_nop 7
	global_store_dword v[18:19], v0, off offset:2368
	global_store_dword v[18:19], v1, off offset:2624
	global_store_dword v[18:19], v2, off offset:2880
	global_store_dword v[18:19], v3, off offset:3136
	ds_read_b128 v[0:3], v5 offset:5632
	ds_read_b128 v[14:17], v5 offset:5696
	s_waitcnt lgkmcnt(1)
	v_mfma_f32_16x16x32_bf16 v[0:3], v[116:119], v[0:3], 0
	s_waitcnt lgkmcnt(0)
	v_mfma_f32_16x16x32_bf16 v[0:3], v[120:123], v[14:17], v[0:3]
	s_nop 7
	global_store_dword v[18:19], v0, off offset:2432
	global_store_dword v[18:19], v1, off offset:2688
	global_store_dword v[18:19], v2, off offset:2944
	global_store_dword v[18:19], v3, off offset:3200
	ds_read_b128 v[0:3], v5 offset:7936
	s_waitcnt lgkmcnt(0)
	v_mfma_f32_16x16x32_bf16 v[0:3], v[116:119], v[0:3], 0
	ds_read_b128 v[4:7], v5 offset:8000
	s_waitcnt lgkmcnt(0)
	v_mfma_f32_16x16x32_bf16 v[0:3], v[120:123], v[4:7], v[0:3]
	s_nop 7
	global_store_dword v[18:19], v0, off offset:2496
	global_store_dword v[18:19], v1, off offset:2752
	global_store_dword v[18:19], v2, off offset:3008
	global_store_dword v[18:19], v3, off offset:3264
	s_barrier
	s_cbranch_scc1 .LBB0_272
